# rwkv_apply rewritten by hand: loader waves fill a 4-slot half-group LDS ring by LDS-DMA (3 half-groups in flight), consumer waves run one chunk per step with operands of the next chunk prefetched, no
# speedup vs baseline: 1.0040x; 1.0040x over previous
.LBB0_1020:
	s_and_b64 vcc, exec, s[0:1]
	s_cbranch_vccz .LBB0_1045
	s_ashr_i32 s4, s2, 4
	s_lshl_b32 s0, s2, 6
	s_ashr_i32 s5, s4, 31
	s_and_b32 s3, s0, 0x3c0
	s_cmpk_lt_u32 s33, 0x100
	s_mov_b64 s[0:1], -1
	s_cbranch_scc0 .LBB0_1025
	s_lshl_b32 s17, s57, 4
	v_or_b32_e32 v0, s3, v133
	v_or_b32_e32 v0, s17, v0
	v_mov_b32_e32 v2, 0
	v_lshlrev_b32_e32 v0, 2, v0
	v_mov_b32_e32 v1, v2
	v_lshl_add_u64 v[0:1], s[40:41], 0, v[0:1]
	v_add_co_u32_e32 v0, vcc, 0x2000, v0
	s_and_b32 s18, s2, 15
	s_nop 0
	v_addc_co_u32_e32 v1, vcc, 0, v1, vcc
	global_load_dword v76, v[0:1], off
	s_lshr_b32 s19, s33, 1
	s_lshl_b64 s[0:1], s[4:5], 23
	s_lshl_b32 s18, s18, 7
	s_and_b32 s19, s19, 0x7fffffe0
	s_add_u32 s18, s19, s18
	s_addc_u32 s19, 0, 0
	v_lshlrev_b32_e32 v0, 5, v146
	v_and_b32_e32 v1, 48, v144
	s_add_u32 s0, s18, s0
	s_waitcnt vmcnt(12)
	v_and_b32_e32 v85, 0x600, v0
	v_lshlrev_b32_e32 v0, 9, v1
	v_mov_b32_e32 v1, v2
	s_addc_u32 s1, s19, s1
	s_waitcnt lgkmcnt(0)
	s_barrier
	v_lshl_add_u64 v[0:1], s[0:1], 0, v[0:1]
	v_lshl_or_b32 v0, v133, 1, v0
	s_mov_b32 s8, 0
	s_waitcnt vmcnt(1)
	v_lshlrev_b32_e32 v82, 4, v146
	v_lshlrev_b32_e32 v83, 3, v146
	v_cmp_gt_u32_e32 vcc, 16, v146
	s_mov_b64 s[6:7], 0
	v_lshlrev_b32_e32 v84, 1, v133
	s_movk_i32 s5, 0x7fff
	s_brev_b32 s9, 16
	s_mov_b32 s10, 0x8001000
	s_mov_b32 s11, 0x8008000
	s_mov_b32 s12, 0x8009000
	s_mov_b32 s13, 0x8010000
	s_mov_b32 s14, 0x8011000
	s_mov_b32 s15, 0x8018000
	s_mov_b32 s16, 0x8019000
	v_mov_b32_e32 v44, v2
	v_mov_b32_e32 v45, v2
	v_mov_b32_e32 v46, v2
	v_mov_b32_e32 v47, v2
	v_mov_b32_e32 v48, v2
	v_mov_b32_e32 v49, v2
	v_mov_b32_e32 v50, v2
	v_mov_b32_e32 v51, v2
	v_mov_b32_e32 v28, v2
	v_mov_b32_e32 v29, v2
	v_mov_b32_e32 v30, v2
	v_mov_b32_e32 v31, v2
	v_mov_b32_e32 v36, v2
	v_mov_b32_e32 v37, v2
	v_mov_b32_e32 v38, v2
	s_lshl_b32 s17, s17, 1
	v_lshl_add_u64 v[78:79], s[52:53], 0, v[0:1]
	v_mov_b32_e32 v39, v2
	s_waitcnt vmcnt(0)
	v_mov_b32_e32 v77, v76
	v_lshlrev_b32_e32 v150, 4, v146
	v_lshlrev_b32_e32 v151, 3, v146
	v_lshrrev_b32_e32 v216, 4, v146
	v_and_b32_e32 v217, 15, v146
	s_lshl_b32 s12, s57, 5
	v_lshlrev_b32_e32 v152, 9, v216
	v_lshl_add_u32 v152, v217, 1, v152
	v_add_u32_e32 v152, s12, v152
	s_lshr_b32 s12, s2, 4
	s_lshl_b32 s12, s12, 22
	s_and_b32 s13, s2, 15
	s_lshl_b32 s13, s13, 6
	s_add_u32 s12, s12, s13
	s_lshl_b32 s13, s57, 4
	s_add_u32 s12, s12, s13
	v_lshl_add_u32 v153, v216, 12, v217
	v_add_u32_e32 v153, s12, v153
	v_lshlrev_b32_e32 v153, 1, v153
	s_add_u32 s6, s52, 0x8000000
	s_addc_u32 s7, s53, 0
	v_mov_b32_e32 v46, 0
	v_mov_b32_e32 v47, 0
	v_mov_b32_e32 v50, 0
	v_mov_b32_e32 v51, 0
	v_mov_b32_e32 v54, 0
	v_mov_b32_e32 v55, 0
	v_mov_b32_e32 v58, 0
	v_mov_b32_e32 v59, 0
	v_mov_b32_e32 v62, 0
	v_mov_b32_e32 v63, 0
	v_mov_b32_e32 v64, 0
	v_mov_b32_e32 v65, 0
	v_mov_b32_e32 v66, 0
	v_mov_b32_e32 v67, 0
	v_mov_b32_e32 v68, 0
	v_mov_b32_e32 v122, 0
	v_mov_b32_e32 v123, 0
	v_mov_b32_e32 v126, 0
	v_mov_b32_e32 v127, 0
	v_mov_b32_e32 v130, 0
	v_mov_b32_e32 v131, 0
	v_mov_b32_e32 v142, 0
	v_mov_b32_e32 v143, 0
	v_mov_b32_e32 v158, 0
	v_mov_b32_e32 v159, 0
	v_mov_b32_e32 v160, 0
	v_mov_b32_e32 v161, 0
	v_mov_b32_e32 v162, 0
	v_mov_b32_e32 v163, 0
	v_mov_b32_e32 v164, 0
	v_mov_b32_e32 v214, 0
	v_mov_b32_e32 v215, 0
	v_mov_b32_e32 v204, 0
	v_mov_b32_e32 v205, 0
	v_mov_b32_e32 v206, 0
	v_mov_b32_e32 v207, 0
	v_mov_b32_e32 v208, 0
	v_mov_b32_e32 v209, 0
	v_mov_b32_e32 v210, 0
	v_mov_b32_e32 v211, 0
	s_mov_b32 s4, 0
	s_lshr_b32 s5, s4, 1
	s_and_b32 s5, s5, 3
	s_mul_i32 s5, s5, 29952
	s_and_b32 s12, s4, 1
	s_mul_i32 s12, s12, 14976
	s_add_u32 s5, s5, s12
	v_add_u32_e32 v157, s5, v152
	v_add_u32_e32 v155, s5, v151
	v_add_u32_e32 v154, s5, v150
	ds_read_u16_d16_hi v64, v157 offset:12800
	ds_read_u16_d16_hi v65, v157 offset:12928
	ds_read_u16_d16_hi v66, v157 offset:13056
	ds_read_u16_d16_hi v67, v157 offset:13184
	ds_read_u16_d16_hi v68, v157 offset:13312
	ds_read_b64 v[60:61], v155 offset:12288
	ds_read_b64 v[44:45], v155 offset:8192
	ds_read_b64 v[48:49], v155 offset:8704
	ds_read_b64 v[52:53], v155 offset:9216
	ds_read_b64 v[56:57], v155 offset:9728
	ds_read_b128 v[36:39], v154 offset:10240
	ds_read_b128 v[40:43], v154 offset:11264
	ds_read_b128 v[4:7], v154 offset:0
	ds_read_b128 v[8:11], v154 offset:1024
	ds_read_b128 v[12:15], v154 offset:2048
	ds_read_b128 v[16:19], v154 offset:3072
	ds_read_b128 v[20:23], v154 offset:4096
	ds_read_b128 v[24:27], v154 offset:5120
	ds_read_b128 v[28:31], v154 offset:6144
	ds_read_b128 v[32:35], v154 offset:7168
	s_waitcnt lgkmcnt(0)
	s_mov_b64 exec, 0xffff
	v_mov_b32_e32 v64, 0
	s_mov_b64 exec, -1
	v_sub_f32_e32 v216, v64, v65
	v_sub_f32_e32 v217, v65, v66
	v_sub_f32_e32 v218, v66, v67
	v_sub_f32_e32 v219, v67, v68
	v_fma_f32 v216, v76, v216, v65
	v_fma_f32 v217, v76, v217, v66
	v_fma_f32 v218, v76, v218, v67
	v_fma_f32 v219, v76, v219, v68
	v_cvt_pk_bf16_f32 v212, v216, v217
	v_cvt_pk_bf16_f32 v213, v218, v219
	s_nop 1
	v_mfma_f32_16x16x32_bf16 v[200:203], v[60:63], v[212:215], 0
	v_mfma_f32_16x16x32_bf16 v[168:171], v[44:47], v[212:215], 0
	v_mfma_f32_16x16x32_bf16 v[172:175], v[48:51], v[212:215], 0
	v_mfma_f32_16x16x32_bf16 v[176:179], v[52:55], v[212:215], 0
	v_mfma_f32_16x16x32_bf16 v[180:183], v[56:59], v[212:215], 0
.Lapc_loop:
	s_add_u32 s13, s4, 1
	s_lshr_b32 s5, s13, 1
	s_and_b32 s5, s5, 3
	s_mul_i32 s5, s5, 29952
	s_and_b32 s12, s13, 1
	s_mul_i32 s12, s12, 14976
	s_add_u32 s5, s5, s12
	v_add_u32_e32 v157, s5, v152
	v_add_u32_e32 v155, s5, v151
	v_add_u32_e32 v154, s5, v150
	ds_read_u16_d16_hi v160, v157 offset:12800
	ds_read_u16_d16_hi v161, v157 offset:12928
	ds_read_u16_d16_hi v162, v157 offset:13056
	ds_read_u16_d16_hi v163, v157 offset:13184
	ds_read_u16_d16_hi v164, v157 offset:13312
	ds_read_b64 v[156:157], v155 offset:12288
	ds_read_b64 v[120:121], v155 offset:8192
	ds_read_b64 v[124:125], v155 offset:8704
	ds_read_b64 v[128:129], v155 offset:9216
	ds_read_b64 v[140:141], v155 offset:9728
	ds_read_b128 v[112:115], v154 offset:10240
	ds_read_b128 v[116:119], v154 offset:11264
	ds_read_b128 v[80:83], v154 offset:0
	ds_read_b128 v[84:87], v154 offset:1024
	ds_read_b128 v[88:91], v154 offset:2048
	ds_read_b128 v[92:95], v154 offset:3072
	ds_read_b128 v[96:99], v154 offset:4096
	ds_read_b128 v[100:103], v154 offset:5120
	ds_read_b128 v[104:107], v154 offset:6144
	ds_read_b128 v[108:111], v154 offset:7168
	v_mfma_f32_16x16x32_bf16 v[200:203], v[36:39], v[204:207], v[200:203]
	v_mfma_f32_16x16x32_bf16 v[168:171], v[4:7], v[204:207], v[168:171]
	v_mfma_f32_16x16x32_bf16 v[172:175], v[12:15], v[204:207], v[172:175]
	v_mfma_f32_16x16x32_bf16 v[176:179], v[20:23], v[204:207], v[176:179]
	v_mfma_f32_16x16x32_bf16 v[180:183], v[28:31], v[204:207], v[180:183]
	v_mfma_f32_16x16x32_bf16 v[200:203], v[40:43], v[208:211], v[200:203]
	v_mfma_f32_16x16x32_bf16 v[168:171], v[8:11], v[208:211], v[168:171]
	v_mfma_f32_16x16x32_bf16 v[172:175], v[16:19], v[208:211], v[172:175]
	v_mfma_f32_16x16x32_bf16 v[176:179], v[24:27], v[208:211], v[176:179]
	v_mfma_f32_16x16x32_bf16 v[180:183], v[32:35], v[208:211], v[180:183]
	s_waitcnt lgkmcnt(15)
	v_sub_f32_e32 v216, v160, v161
	v_sub_f32_e32 v217, v161, v162
	v_sub_f32_e32 v218, v162, v163
	v_sub_f32_e32 v219, v163, v164
	v_fma_f32 v216, v76, v216, v161
	v_fma_f32 v217, v76, v217, v162
	v_fma_f32 v218, v76, v218, v163
	v_fma_f32 v219, v76, v219, v164
	v_cvt_pk_bf16_f32 v212, v216, v217
	v_cvt_pk_bf16_f32 v213, v218, v219
	s_waitcnt lgkmcnt(10)
	s_nop 1
	v_mfma_f32_16x16x32_bf16 v[224:227], v[156:159], v[212:215], 0
	v_mfma_f32_16x16x32_bf16 v[184:187], v[120:123], v[212:215], 0
	v_mfma_f32_16x16x32_bf16 v[188:191], v[124:127], v[212:215], 0
	v_mfma_f32_16x16x32_bf16 v[192:195], v[128:131], v[212:215], 0
	v_mfma_f32_16x16x32_bf16 v[196:199], v[140:143], v[212:215], 0
	v_cvt_pk_bf16_f32 v220, v200, v201
	v_cvt_pk_bf16_f32 v221, v202, v203
	s_lshl_b32 s12, s4, 15
	s_add_u32 s8, s6, s12
	s_addc_u32 s9, s7, 0
	s_add_u32 s10, s8, 0x1000
	s_addc_u32 s11, s9, 0
	global_store_short v153, v220, s[8:9]
	global_store_short_d16_hi v153, v220, s[8:9] offset:2048
	global_store_short v153, v221, s[10:11]
	global_store_short_d16_hi v153, v221, s[10:11] offset:2048
	v_cvt_pk_bf16_f32 v204, v168, v169
	v_cvt_pk_bf16_f32 v205, v170, v171
	v_cvt_pk_bf16_f32 v206, v172, v173
	v_cvt_pk_bf16_f32 v207, v174, v175
	v_cvt_pk_bf16_f32 v208, v176, v177
	v_cvt_pk_bf16_f32 v209, v178, v179
	v_cvt_pk_bf16_f32 v210, v180, v181
	v_cvt_pk_bf16_f32 v211, v182, v183
	s_waitcnt lgkmcnt(0)
	s_barrier
	s_add_u32 s4, s4, 2
	s_cmp_lt_u32 s4, 256
	s_cbranch_scc0 .Lapc_last
	s_lshr_b32 s5, s4, 1
	s_and_b32 s5, s5, 3
	s_mul_i32 s5, s5, 29952
	s_and_b32 s12, s4, 1
	s_mul_i32 s12, s12, 14976
	s_add_u32 s5, s5, s12
	v_add_u32_e32 v157, s5, v152
	v_add_u32_e32 v155, s5, v151
	v_add_u32_e32 v154, s5, v150
	ds_read_u16_d16_hi v64, v157 offset:12800
	ds_read_u16_d16_hi v65, v157 offset:12928
	ds_read_u16_d16_hi v66, v157 offset:13056
	ds_read_u16_d16_hi v67, v157 offset:13184
	ds_read_u16_d16_hi v68, v157 offset:13312
	ds_read_b64 v[60:61], v155 offset:12288
	ds_read_b64 v[44:45], v155 offset:8192
	ds_read_b64 v[48:49], v155 offset:8704
	ds_read_b64 v[52:53], v155 offset:9216
	ds_read_b64 v[56:57], v155 offset:9728
	ds_read_b128 v[36:39], v154 offset:10240
	ds_read_b128 v[40:43], v154 offset:11264
	ds_read_b128 v[4:7], v154 offset:0
	ds_read_b128 v[8:11], v154 offset:1024
	ds_read_b128 v[12:15], v154 offset:2048
	ds_read_b128 v[16:19], v154 offset:3072
	ds_read_b128 v[20:23], v154 offset:4096
	ds_read_b128 v[24:27], v154 offset:5120
	ds_read_b128 v[28:31], v154 offset:6144
	ds_read_b128 v[32:35], v154 offset:7168
	v_mfma_f32_16x16x32_bf16 v[224:227], v[112:115], v[204:207], v[224:227]
	v_mfma_f32_16x16x32_bf16 v[184:187], v[80:83], v[204:207], v[184:187]
	v_mfma_f32_16x16x32_bf16 v[188:191], v[88:91], v[204:207], v[188:191]
	v_mfma_f32_16x16x32_bf16 v[192:195], v[96:99], v[204:207], v[192:195]
	v_mfma_f32_16x16x32_bf16 v[196:199], v[104:107], v[204:207], v[196:199]
	v_mfma_f32_16x16x32_bf16 v[224:227], v[116:119], v[208:211], v[224:227]
	v_mfma_f32_16x16x32_bf16 v[184:187], v[84:87], v[208:211], v[184:187]
	v_mfma_f32_16x16x32_bf16 v[188:191], v[92:95], v[208:211], v[188:191]
	v_mfma_f32_16x16x32_bf16 v[192:195], v[100:103], v[208:211], v[192:195]
	v_mfma_f32_16x16x32_bf16 v[196:199], v[108:111], v[208:211], v[196:199]
	s_waitcnt lgkmcnt(15)
	v_sub_f32_e32 v216, v64, v65
	v_sub_f32_e32 v217, v65, v66
	v_sub_f32_e32 v218, v66, v67
	v_sub_f32_e32 v219, v67, v68
	v_fma_f32 v216, v76, v216, v65
	v_fma_f32 v217, v76, v217, v66
	v_fma_f32 v218, v76, v218, v67
	v_fma_f32 v219, v76, v219, v68
	v_cvt_pk_bf16_f32 v212, v216, v217
	v_cvt_pk_bf16_f32 v213, v218, v219
	s_waitcnt lgkmcnt(10)
	s_nop 1
	v_mfma_f32_16x16x32_bf16 v[200:203], v[60:63], v[212:215], 0
	v_mfma_f32_16x16x32_bf16 v[168:171], v[44:47], v[212:215], 0
	v_mfma_f32_16x16x32_bf16 v[172:175], v[48:51], v[212:215], 0
	v_mfma_f32_16x16x32_bf16 v[176:179], v[52:55], v[212:215], 0
	v_mfma_f32_16x16x32_bf16 v[180:183], v[56:59], v[212:215], 0
	v_cvt_pk_bf16_f32 v220, v224, v225
	v_cvt_pk_bf16_f32 v221, v226, v227
	s_lshl_b32 s12, s13, 15
	s_add_u32 s8, s6, s12
	s_addc_u32 s9, s7, 0
	s_add_u32 s10, s8, 0x1000
	s_addc_u32 s11, s9, 0
	global_store_short v153, v220, s[8:9]
	global_store_short_d16_hi v153, v220, s[8:9] offset:2048
	global_store_short v153, v221, s[10:11]
	global_store_short_d16_hi v153, v221, s[10:11] offset:2048
	v_cvt_pk_bf16_f32 v204, v184, v185
	v_cvt_pk_bf16_f32 v205, v186, v187
	v_cvt_pk_bf16_f32 v206, v188, v189
	v_cvt_pk_bf16_f32 v207, v190, v191
	v_cvt_pk_bf16_f32 v208, v192, v193
	v_cvt_pk_bf16_f32 v209, v194, v195
	v_cvt_pk_bf16_f32 v210, v196, v197
	v_cvt_pk_bf16_f32 v211, v198, v199
	s_waitcnt lgkmcnt(0)
	s_branch .Lapc_loop
.Lapc_last:
	v_mfma_f32_16x16x32_bf16 v[224:227], v[112:115], v[204:207], v[224:227]
	v_mfma_f32_16x16x32_bf16 v[184:187], v[80:83], v[204:207], v[184:187]
	v_mfma_f32_16x16x32_bf16 v[188:191], v[88:91], v[204:207], v[188:191]
	v_mfma_f32_16x16x32_bf16 v[192:195], v[96:99], v[204:207], v[192:195]
	v_mfma_f32_16x16x32_bf16 v[196:199], v[104:107], v[204:207], v[196:199]
	v_mfma_f32_16x16x32_bf16 v[224:227], v[116:119], v[208:211], v[224:227]
	v_mfma_f32_16x16x32_bf16 v[184:187], v[84:87], v[208:211], v[184:187]
	v_mfma_f32_16x16x32_bf16 v[188:191], v[92:95], v[208:211], v[188:191]
	v_mfma_f32_16x16x32_bf16 v[192:195], v[100:103], v[208:211], v[192:195]
	v_mfma_f32_16x16x32_bf16 v[196:199], v[108:111], v[208:211], v[196:199]
	s_nop 15
	v_cvt_pk_bf16_f32 v220, v224, v225
	v_cvt_pk_bf16_f32 v221, v226, v227
	s_lshl_b32 s12, s13, 15
	s_add_u32 s8, s6, s12
	s_addc_u32 s9, s7, 0
	s_add_u32 s10, s8, 0x1000
	s_addc_u32 s11, s9, 0
	global_store_short v153, v220, s[8:9]
	global_store_short_d16_hi v153, v220, s[8:9] offset:2048
	global_store_short v153, v221, s[10:11]
	global_store_short_d16_hi v153, v221, s[10:11] offset:2048

.LBB0_1025:
	s_and_b64 vcc, exec, s[0:1]
	s_cbranch_vccz .LBB0_1045
	s_sub_i32 s3, s57, 4
	s_mul_i32 s15, s2, 0x320000
	s_add_u32 s4, s52, s15
	s_addc_u32 s5, s53, 0
	s_add_u32 s4, s4, 0x100000
	s_addc_u32 s5, s5, 0
	s_lshl_b32 s10, s3, 10
	s_add_u32 s4, s4, s10
	s_addc_u32 s5, s5, 0
	s_lshr_b32 s15, s2, 4
	s_mul_i32 s15, s15, 0x5400000
	s_and_b32 s20, s2, 15
	s_lshl_b32 s20, s20, 7
	s_add_u32 s15, s15, s20
	s_add_u32 s6, s52, s15
	s_addc_u32 s7, s53, 0
	s_add_u32 s6, s6, 0xdffd400
	s_addc_u32 s7, s7, 0
	v_lshlrev_b32_e32 v0, 4, v146
	s_cmp_eq_u32 s3, 0
	s_cbranch_scc1 .Lld_w0
	s_sub_i32 s15, s3, 1
	s_lshl_b32 s20, s15, 6
	v_add_u32_e32 v1, s20, v146
	v_lshrrev_b32_e32 v2, 3, v1
	v_and_b32_e32 v1, 7, v1
	v_mul_u32_u24_e32 v2, 0x5400, v2
	v_lshl_add_u32 v1, v1, 4, v2
	s_mov_b32 s8, 0x54000
	s_lshl_b32 s9, s15, 10
	s_add_u32 s9, s9, 0x3200
	s_mov_b64 s[12:13], -1
	s_cmp_eq_u32 s3, 3
	s_cselect_b32 s12, 0xff, s12
	s_cselect_b32 s13, 0, s13
	s_branch .Lld_wdone
.Lld_w0:
	v_lshlrev_b32_e32 v1, 4, v146
	s_add_u32 s6, s4, 0x3000
	s_addc_u32 s7, s5, 0
	s_mov_b32 s8, 0x3200
	s_mov_b32 s9, 0x3000
	s_mov_b32 s12, -1
	s_mov_b32 s13, 0
.Lld_wdone:
	s_mov_b32 s15, 0
	s_and_b32 s22, s15, 3
	s_mul_i32 s22, s22, 29952
	s_lshl_b32 s20, s15, 1
	s_mul_i32 s23, s20, 0x3200
	s_add_u32 s28, s4, s23
	s_addc_u32 s29, s5, 0
	s_mul_i32 s23, s20, s8
	s_add_u32 s64, s6, s23
	s_addc_u32 s65, s7, 0
	s_add_u32 s26, s22, s10
	s_mov_b32 m0, s26
	s_nop 0
	global_load_lds_dwordx4 v0, s[28:29]
	s_add_u32 s28, s28, 0x1000
	s_addc_u32 s29, s29, 0
	s_add_i32 m0, s26, 0x1000
	s_nop 0
	global_load_lds_dwordx4 v0, s[28:29]
	s_add_u32 s28, s28, 0x1000
	s_addc_u32 s29, s29, 0
	s_add_i32 m0, s26, 0x2000
	s_nop 0
	global_load_lds_dwordx4 v0, s[28:29]
	s_add_i32 m0, s22, s9
	s_mov_b64 exec, s[12:13]
	global_load_lds_dwordx4 v1, s[64:65]
	s_mov_b64 exec, -1
	s_add_u32 s20, s20, 1
	s_add_u32 s22, s22, 14976
	s_mul_i32 s23, s20, 0x3200
	s_add_u32 s28, s4, s23
	s_addc_u32 s29, s5, 0
	s_mul_i32 s23, s20, s8
	s_add_u32 s64, s6, s23
	s_addc_u32 s65, s7, 0
	s_add_u32 s26, s22, s10
	s_mov_b32 m0, s26
	s_nop 0
	global_load_lds_dwordx4 v0, s[28:29]
	s_add_u32 s28, s28, 0x1000
	s_addc_u32 s29, s29, 0
	s_add_i32 m0, s26, 0x1000
	s_nop 0
	global_load_lds_dwordx4 v0, s[28:29]
	s_add_u32 s28, s28, 0x1000
	s_addc_u32 s29, s29, 0
	s_add_i32 m0, s26, 0x2000
	s_nop 0
	global_load_lds_dwordx4 v0, s[28:29]
	s_add_i32 m0, s22, s9
	s_mov_b64 exec, s[12:13]
	global_load_lds_dwordx4 v1, s[64:65]
	s_mov_b64 exec, -1
	s_mov_b32 s15, 1
	s_and_b32 s22, s15, 3
	s_mul_i32 s22, s22, 29952
	s_lshl_b32 s20, s15, 1
	s_mul_i32 s23, s20, 0x3200
	s_add_u32 s28, s4, s23
	s_addc_u32 s29, s5, 0
	s_mul_i32 s23, s20, s8
	s_add_u32 s64, s6, s23
	s_addc_u32 s65, s7, 0
	s_add_u32 s26, s22, s10
	s_mov_b32 m0, s26
	s_nop 0
	global_load_lds_dwordx4 v0, s[28:29]
	s_add_u32 s28, s28, 0x1000
	s_addc_u32 s29, s29, 0
	s_add_i32 m0, s26, 0x1000
	s_nop 0
	global_load_lds_dwordx4 v0, s[28:29]
	s_add_u32 s28, s28, 0x1000
	s_addc_u32 s29, s29, 0
	s_add_i32 m0, s26, 0x2000
	s_nop 0
	global_load_lds_dwordx4 v0, s[28:29]
	s_add_i32 m0, s22, s9
	s_mov_b64 exec, s[12:13]
	global_load_lds_dwordx4 v1, s[64:65]
	s_mov_b64 exec, -1
	s_add_u32 s20, s20, 1
	s_add_u32 s22, s22, 14976
	s_mul_i32 s23, s20, 0x3200
	s_add_u32 s28, s4, s23
	s_addc_u32 s29, s5, 0
	s_mul_i32 s23, s20, s8
	s_add_u32 s64, s6, s23
	s_addc_u32 s65, s7, 0
	s_add_u32 s26, s22, s10
	s_mov_b32 m0, s26
	s_nop 0
	global_load_lds_dwordx4 v0, s[28:29]
	s_add_u32 s28, s28, 0x1000
	s_addc_u32 s29, s29, 0
	s_add_i32 m0, s26, 0x1000
	s_nop 0
	global_load_lds_dwordx4 v0, s[28:29]
	s_add_u32 s28, s28, 0x1000
	s_addc_u32 s29, s29, 0
	s_add_i32 m0, s26, 0x2000
	s_nop 0
	global_load_lds_dwordx4 v0, s[28:29]
	s_add_i32 m0, s22, s9
	s_mov_b64 exec, s[12:13]
	global_load_lds_dwordx4 v1, s[64:65]
	s_mov_b64 exec, -1
	s_mov_b32 s15, 2
	s_and_b32 s22, s15, 3
	s_mul_i32 s22, s22, 29952
	s_lshl_b32 s20, s15, 1
	s_mul_i32 s23, s20, 0x3200
	s_add_u32 s28, s4, s23
	s_addc_u32 s29, s5, 0
	s_mul_i32 s23, s20, s8
	s_add_u32 s64, s6, s23
	s_addc_u32 s65, s7, 0
	s_add_u32 s26, s22, s10
	s_mov_b32 m0, s26
	s_nop 0
	global_load_lds_dwordx4 v0, s[28:29]
	s_add_u32 s28, s28, 0x1000
	s_addc_u32 s29, s29, 0
	s_add_i32 m0, s26, 0x1000
	s_nop 0
	global_load_lds_dwordx4 v0, s[28:29]
	s_add_u32 s28, s28, 0x1000
	s_addc_u32 s29, s29, 0
	s_add_i32 m0, s26, 0x2000
	s_nop 0
	global_load_lds_dwordx4 v0, s[28:29]
	s_add_i32 m0, s22, s9
	s_mov_b64 exec, s[12:13]
	global_load_lds_dwordx4 v1, s[64:65]
	s_mov_b64 exec, -1
	s_add_u32 s20, s20, 1
	s_add_u32 s22, s22, 14976
	s_mul_i32 s23, s20, 0x3200
	s_add_u32 s28, s4, s23
	s_addc_u32 s29, s5, 0
	s_mul_i32 s23, s20, s8
	s_add_u32 s64, s6, s23
	s_addc_u32 s65, s7, 0
	s_add_u32 s26, s22, s10
	s_mov_b32 m0, s26
	s_nop 0
	global_load_lds_dwordx4 v0, s[28:29]
	s_add_u32 s28, s28, 0x1000
	s_addc_u32 s29, s29, 0
	s_add_i32 m0, s26, 0x1000
	s_nop 0
	global_load_lds_dwordx4 v0, s[28:29]
	s_add_u32 s28, s28, 0x1000
	s_addc_u32 s29, s29, 0
	s_add_i32 m0, s26, 0x2000
	s_nop 0
	global_load_lds_dwordx4 v0, s[28:29]
	s_add_i32 m0, s22, s9
	s_mov_b64 exec, s[12:13]
	global_load_lds_dwordx4 v1, s[64:65]
	s_mov_b64 exec, -1
	s_waitcnt vmcnt(16)
	s_barrier
	s_mov_b32 s14, 0
.Lld_loop:
	s_add_u32 s15, s14, 3
	s_cmp_gt_u32 s15, 127
	s_cbranch_scc1 .Lld_tail
	s_and_b32 s22, s15, 3
	s_mul_i32 s22, s22, 29952
	s_lshl_b32 s20, s15, 1
	s_mul_i32 s23, s20, 0x3200
	s_add_u32 s28, s4, s23
	s_addc_u32 s29, s5, 0
	s_mul_i32 s23, s20, s8
	s_add_u32 s64, s6, s23
	s_addc_u32 s65, s7, 0
	s_add_u32 s26, s22, s10
	s_mov_b32 m0, s26
	s_nop 0
	global_load_lds_dwordx4 v0, s[28:29]
	s_add_u32 s28, s28, 0x1000
	s_addc_u32 s29, s29, 0
	s_add_i32 m0, s26, 0x1000
	s_nop 0
	global_load_lds_dwordx4 v0, s[28:29]
	s_add_u32 s28, s28, 0x1000
	s_addc_u32 s29, s29, 0
	s_add_i32 m0, s26, 0x2000
	s_nop 0
	global_load_lds_dwordx4 v0, s[28:29]
	s_add_i32 m0, s22, s9
	s_mov_b64 exec, s[12:13]
	global_load_lds_dwordx4 v1, s[64:65]
	s_mov_b64 exec, -1
	s_add_u32 s20, s20, 1
	s_add_u32 s22, s22, 14976
	s_mul_i32 s23, s20, 0x3200
	s_add_u32 s28, s4, s23
	s_addc_u32 s29, s5, 0
	s_mul_i32 s23, s20, s8
	s_add_u32 s64, s6, s23
	s_addc_u32 s65, s7, 0
	s_add_u32 s26, s22, s10
	s_mov_b32 m0, s26
	s_nop 0
	global_load_lds_dwordx4 v0, s[28:29]
	s_add_u32 s28, s28, 0x1000
	s_addc_u32 s29, s29, 0
	s_add_i32 m0, s26, 0x1000
	s_nop 0
	global_load_lds_dwordx4 v0, s[28:29]
	s_add_u32 s28, s28, 0x1000
	s_addc_u32 s29, s29, 0
	s_add_i32 m0, s26, 0x2000
	s_nop 0
	global_load_lds_dwordx4 v0, s[28:29]
	s_add_i32 m0, s22, s9
	s_mov_b64 exec, s[12:13]
	global_load_lds_dwordx4 v1, s[64:65]
	s_mov_b64 exec, -1
	s_waitcnt vmcnt(16)
	s_branch .Lld_bar

.Lld_bar:
	s_barrier
	s_add_u32 s14, s14, 1
	s_cmp_lt_u32 s14, 128
	s_cbranch_scc1 .Lld_loop
